# selected-branch lookup-bias tiles: both column blocks' softmax streams interleaved as well (second block's bias reads issued under the first block's max reduction)
# baseline (speedup 1.0000x reference)
.LBB0_430:
	s_andn2_b64 vcc, exec, s[6:7]
	s_cbranch_vccnz .LBB0_438
	v_cmp_ne_u32_e32 vcc, 0, v139
	s_cbranch_vccz .Lsel_fast
	v_add_u32_e32 v54, s13, v196
	v_sub_u32_e32 v0, s14, v140
	v_add_u32_e32 v62, v54, v194
	v_add_u32_e32 v89, v54, v195
	v_lshl_add_u32 v0, v0, 2, v216
	s_cmp_lg_u64 s[44:45], 0
	s_movk_i32 s98, 0xfec
	s_cselect_b32 s98, 0xffc, s98
	v_add_u32_e32 v230, s98, v0
	v_add_u32_e32 v231, 0xfec, v0
	ds_read_b128 v[64:67], v62 offset:16384
	ds_read_b128 v[54:57], v89 offset:16384
	ds_read_b128 v[68:71], v62 offset:18432
	ds_read_b128 v[58:61], v89 offset:18432
	ds_read_b128 v[72:75], v62 offset:20480
	ds_read_b128 v[76:79], v89 offset:20480
	ds_read_b128 v[80:83], v62 offset:22528
	ds_read_b128 v[84:87], v89 offset:22528
	ds_read2_b32 v[90:91], v230 offset1:1
	ds_read2_b32 v[92:93], v230 offset0:2 offset1:3
	ds_read2_b32 v[94:95], v230 offset0:16 offset1:17
	ds_read2_b32 v[96:97], v230 offset0:18 offset1:19
	s_waitcnt lgkmcnt(4)
	ds_read2_b32 v[98:99], v230 offset0:32 offset1:33
	ds_read2_b32 v[100:101], v230 offset0:34 offset1:35
	ds_read2_b32 v[154:155], v230 offset0:48 offset1:49
	ds_read2_b32 v[156:157], v230 offset0:50 offset1:51
	s_cbranch_scc0 .Lp1v_m1
	s_cmp_lg_u64 s[42:43], 0
	s_cbranch_scc0 .Lp1v_only0
	s_setprio 1
	v_mfma_f32_16x16x32_bf16 v[170:173], v[64:67], v[2:5], 0
	v_mfma_f32_16x16x32_bf16 v[174:177], v[68:71], v[2:5], 0
	v_mfma_f32_16x16x32_bf16 v[170:173], v[54:57], v[6:9], v[170:173]
	v_mfma_f32_16x16x32_bf16 v[178:181], v[72:75], v[2:5], 0
	v_mfma_f32_16x16x32_bf16 v[174:177], v[58:61], v[6:9], v[174:177]
	v_mfma_f32_16x16x32_bf16 v[182:185], v[80:83], v[2:5], 0
	v_mfma_f32_16x16x32_bf16 v[178:181], v[76:79], v[6:9], v[178:181]
	v_mfma_f32_16x16x32_bf16 v[182:185], v[84:87], v[6:9], v[182:185]
	v_mfma_f32_16x16x32_bf16 v[64:67], v[64:67], v[10:13], 0
	v_mfma_f32_16x16x32_bf16 v[68:71], v[68:71], v[10:13], 0
	v_mfma_f32_16x16x32_bf16 v[64:67], v[54:57], v[14:17], v[64:67]
	v_mfma_f32_16x16x32_bf16 v[72:75], v[72:75], v[10:13], 0
	v_mfma_f32_16x16x32_bf16 v[68:71], v[58:61], v[14:17], v[68:71]
	v_mfma_f32_16x16x32_bf16 v[80:83], v[80:83], v[10:13], 0
	v_mfma_f32_16x16x32_bf16 v[72:75], v[76:79], v[14:17], v[72:75]
	v_mfma_f32_16x16x32_bf16 v[80:83], v[84:87], v[14:17], v[80:83]
	s_setprio 0
	s_waitcnt lgkmcnt(0)
	v_pk_fma_f32 v[170:171], v[170:171], s[36:37], v[90:91] op_sel_hi:[1,0,1]
	v_pk_fma_f32 v[172:173], v[172:173], s[36:37], v[92:93] op_sel_hi:[1,0,1]
	v_pk_fma_f32 v[174:175], v[174:175], s[36:37], v[94:95] op_sel_hi:[1,0,1]
	v_pk_fma_f32 v[176:177], v[176:177], s[36:37], v[96:97] op_sel_hi:[1,0,1]
	v_pk_fma_f32 v[178:179], v[178:179], s[36:37], v[98:99] op_sel_hi:[1,0,1]
	v_pk_fma_f32 v[180:181], v[180:181], s[36:37], v[100:101] op_sel_hi:[1,0,1]
	v_pk_fma_f32 v[182:183], v[182:183], s[36:37], v[154:155] op_sel_hi:[1,0,1]
	v_pk_fma_f32 v[184:185], v[184:185], s[36:37], v[156:157] op_sel_hi:[1,0,1]
	ds_read2_b32 v[90:91], v231 offset1:1
	ds_read2_b32 v[92:93], v231 offset0:2 offset1:3
	ds_read2_b32 v[94:95], v231 offset0:16 offset1:17
	ds_read2_b32 v[96:97], v231 offset0:18 offset1:19
	ds_read2_b32 v[98:99], v231 offset0:32 offset1:33
	ds_read2_b32 v[100:101], v231 offset0:34 offset1:35
	ds_read2_b32 v[154:155], v231 offset0:48 offset1:49
	ds_read2_b32 v[156:157], v231 offset0:50 offset1:51
	v_max3_f32 v186, v170, v171, v172
	v_max3_f32 v186, v186, v173, v174
	v_max3_f32 v186, v186, v175, v176
	v_max3_f32 v186, v186, v177, v178
	v_max3_f32 v186, v186, v179, v180
	v_max3_f32 v186, v186, v181, v182
	v_max3_f32 v186, v186, v183, v184
	v_max3_f32 v186, v186, v185, s29
	v_mov_b32_e32 v187, v186
	s_nop 1
	v_permlane16_swap_b32_e32 v186, v187
	v_max_f32_e32 v186, v186, v187
	v_mov_b32_e32 v187, v186
	s_nop 1
	v_permlane32_swap_b32_e32 v186, v187
	v_max_f32_e32 v186, v186, v187
	v_cndmask_b32_e64 v186, v148, v186, s[44:45]
	v_max_f32_e32 v187, v160, v186
	s_waitcnt lgkmcnt(0)
	v_pk_fma_f32 v[64:65], v[64:65], s[36:37], v[90:91] op_sel_hi:[1,0,1]
	v_pk_fma_f32 v[66:67], v[66:67], s[36:37], v[92:93] op_sel_hi:[1,0,1]
	v_pk_fma_f32 v[68:69], v[68:69], s[36:37], v[94:95] op_sel_hi:[1,0,1]
	v_pk_fma_f32 v[70:71], v[70:71], s[36:37], v[96:97] op_sel_hi:[1,0,1]
	v_pk_fma_f32 v[72:73], v[72:73], s[36:37], v[98:99] op_sel_hi:[1,0,1]
	v_pk_fma_f32 v[74:75], v[74:75], s[36:37], v[100:101] op_sel_hi:[1,0,1]
	v_pk_fma_f32 v[80:81], v[80:81], s[36:37], v[154:155] op_sel_hi:[1,0,1]
	v_pk_fma_f32 v[82:83], v[82:83], s[36:37], v[156:157] op_sel_hi:[1,0,1]
	v_max3_f32 v76, v64, v65, v66
	v_max3_f32 v76, v76, v67, v68
	v_max3_f32 v76, v76, v69, v70
	v_max3_f32 v76, v76, v71, v72
	v_max3_f32 v76, v76, v73, v74
	v_max3_f32 v76, v76, v75, v80
	v_max3_f32 v76, v76, v81, v82
	v_max3_f32 v76, v76, v83, s29
	v_mov_b32_e32 v77, v76
	s_nop 1
	v_permlane16_swap_b32_e32 v76, v77
	v_max_f32_e32 v76, v76, v77
	v_mov_b32_e32 v77, v76
	s_nop 1
	v_permlane32_swap_b32_e32 v76, v77
	v_max_f32_e32 v76, v76, v77
	v_cndmask_b32_e64 v76, v148, v76, s[42:43]
	v_max_f32_e32 v77, v161, v76
	v_sub_f32_e32 v248, v160, v187
	v_sub_f32_e32 v0, v161, v77
	v_exp_f32_e32 v236, v248
	v_exp_f32_e32 v0, v0
	v_cndmask_b32_e64 v246, v209, v187, s[44:45]
	v_cndmask_b32_e64 v78, v209, v77, s[42:43]
	v_mov_b32_e32 v160, v187
	v_mov_b32_e32 v161, v77
	v_pk_mul_f32 v[36:37], v[36:37], v[236:237] op_sel_hi:[1,0]
	v_pk_mul_f32 v[32:33], v[32:33], v[0:1] op_sel_hi:[1,0]
	v_pk_mul_f32 v[34:35], v[34:35], v[236:237] op_sel_hi:[1,0]
	v_pk_mul_f32 v[30:31], v[30:31], v[0:1] op_sel_hi:[1,0]
	v_pk_mul_f32 v[48:49], v[48:49], v[236:237] op_sel_hi:[1,0]
	v_pk_mul_f32 v[28:29], v[28:29], v[0:1] op_sel_hi:[1,0]
	v_pk_mul_f32 v[46:47], v[46:47], v[236:237] op_sel_hi:[1,0]
	v_pk_mul_f32 v[26:27], v[26:27], v[0:1] op_sel_hi:[1,0]
	v_pk_mul_f32 v[44:45], v[44:45], v[236:237] op_sel_hi:[1,0]
	v_pk_mul_f32 v[24:25], v[24:25], v[0:1] op_sel_hi:[1,0]
	v_pk_mul_f32 v[42:43], v[42:43], v[236:237] op_sel_hi:[1,0]
	v_pk_mul_f32 v[22:23], v[22:23], v[0:1] op_sel_hi:[1,0]
	v_pk_mul_f32 v[52:53], v[52:53], v[236:237] op_sel_hi:[1,0]
	v_pk_mul_f32 v[20:21], v[20:21], v[0:1] op_sel_hi:[1,0]
	v_pk_mul_f32 v[50:51], v[50:51], v[236:237] op_sel_hi:[1,0]
	v_pk_mul_f32 v[18:19], v[18:19], v[0:1] op_sel_hi:[1,0]
	v_pk_add_f32 v[170:171], v[170:171], v[246:247] op_sel_hi:[1,0] neg_lo:[0,1] neg_hi:[0,1]
	v_pk_add_f32 v[64:65], v[64:65], v[78:79] op_sel_hi:[1,0] neg_lo:[0,1] neg_hi:[0,1]
	v_pk_add_f32 v[172:173], v[172:173], v[246:247] op_sel_hi:[1,0] neg_lo:[0,1] neg_hi:[0,1]
	v_pk_add_f32 v[66:67], v[66:67], v[78:79] op_sel_hi:[1,0] neg_lo:[0,1] neg_hi:[0,1]
	v_pk_add_f32 v[174:175], v[174:175], v[246:247] op_sel_hi:[1,0] neg_lo:[0,1] neg_hi:[0,1]
	v_pk_add_f32 v[68:69], v[68:69], v[78:79] op_sel_hi:[1,0] neg_lo:[0,1] neg_hi:[0,1]
	v_pk_add_f32 v[176:177], v[176:177], v[246:247] op_sel_hi:[1,0] neg_lo:[0,1] neg_hi:[0,1]
	v_pk_add_f32 v[70:71], v[70:71], v[78:79] op_sel_hi:[1,0] neg_lo:[0,1] neg_hi:[0,1]
	v_pk_add_f32 v[178:179], v[178:179], v[246:247] op_sel_hi:[1,0] neg_lo:[0,1] neg_hi:[0,1]
	v_pk_add_f32 v[72:73], v[72:73], v[78:79] op_sel_hi:[1,0] neg_lo:[0,1] neg_hi:[0,1]
	v_pk_add_f32 v[180:181], v[180:181], v[246:247] op_sel_hi:[1,0] neg_lo:[0,1] neg_hi:[0,1]
	v_pk_add_f32 v[74:75], v[74:75], v[78:79] op_sel_hi:[1,0] neg_lo:[0,1] neg_hi:[0,1]
	v_pk_add_f32 v[182:183], v[182:183], v[246:247] op_sel_hi:[1,0] neg_lo:[0,1] neg_hi:[0,1]
	v_pk_add_f32 v[80:81], v[80:81], v[78:79] op_sel_hi:[1,0] neg_lo:[0,1] neg_hi:[0,1]
	v_pk_add_f32 v[184:185], v[184:185], v[246:247] op_sel_hi:[1,0] neg_lo:[0,1] neg_hi:[0,1]
	v_pk_add_f32 v[82:83], v[82:83], v[78:79] op_sel_hi:[1,0] neg_lo:[0,1] neg_hi:[0,1]
	v_exp_f32_e32 v170, v170
	v_exp_f32_e32 v64, v64
	v_exp_f32_e32 v171, v171
	v_exp_f32_e32 v65, v65
	v_exp_f32_e32 v172, v172
	v_exp_f32_e32 v66, v66
	v_exp_f32_e32 v173, v173
	v_exp_f32_e32 v67, v67
	v_exp_f32_e32 v174, v174
	v_exp_f32_e32 v68, v68
	v_exp_f32_e32 v175, v175
	v_exp_f32_e32 v69, v69
	v_exp_f32_e32 v176, v176
	v_exp_f32_e32 v70, v70
	v_exp_f32_e32 v177, v177
	v_exp_f32_e32 v71, v71
	v_exp_f32_e32 v178, v178
	v_exp_f32_e32 v72, v72
	v_exp_f32_e32 v179, v179
	v_exp_f32_e32 v73, v73
	v_exp_f32_e32 v180, v180
	v_exp_f32_e32 v74, v74
	v_exp_f32_e32 v181, v181
	v_exp_f32_e32 v75, v75
	v_exp_f32_e32 v182, v182
	v_exp_f32_e32 v80, v80
	v_exp_f32_e32 v183, v183
	v_exp_f32_e32 v81, v81
	v_exp_f32_e32 v184, v184
	v_exp_f32_e32 v82, v82
	v_exp_f32_e32 v185, v185
	v_exp_f32_e32 v83, v83
	s_nop 0
	s_nop 0
	v_pk_add_f32 v[238:239], v[170:171], v[172:173]
	v_pk_add_f32 v[84:85], v[64:65], v[66:67]
	v_pk_add_f32 v[240:241], v[174:175], v[176:177]
	v_pk_add_f32 v[86:87], v[68:69], v[70:71]
	v_pk_add_f32 v[242:243], v[178:179], v[180:181]
	v_pk_add_f32 v[76:77], v[72:73], v[74:75]
	v_pk_add_f32 v[244:245], v[182:183], v[184:185]
	v_pk_add_f32 v[78:79], v[80:81], v[82:83]
	v_pk_add_f32 v[238:239], v[238:239], v[240:241]
	v_pk_add_f32 v[84:85], v[84:85], v[86:87]
	v_pk_add_f32 v[242:243], v[242:243], v[244:245]
	v_pk_add_f32 v[76:77], v[76:77], v[78:79]
	s_nop 0
	s_nop 0
	v_pk_add_f32 v[238:239], v[238:239], v[242:243]
	v_pk_add_f32 v[84:85], v[84:85], v[76:77]
	s_nop 0
	s_nop 0
	v_add_f32_e32 v238, v238, v239
	v_add_f32_e32 v84, v84, v85
	v_fma_f32 v144, v144, v236, v238
	v_fma_f32 v145, v145, v0, v84
	v_cvt_pk_bf16_f32 v58, v170, v171
	v_cvt_pk_bf16_f32 v67, v66, v67
	v_cvt_pk_bf16_f32 v59, v172, v173
	v_cvt_pk_bf16_f32 v66, v64, v65
	v_cvt_pk_bf16_f32 v60, v174, v175
	v_cvt_pk_bf16_f32 v68, v68, v69
	v_cvt_pk_bf16_f32 v61, v176, v177
	v_cvt_pk_bf16_f32 v69, v70, v71
	v_cvt_pk_bf16_f32 v54, v178, v179
	v_cvt_pk_bf16_f32 v62, v72, v73
	v_cvt_pk_bf16_f32 v55, v180, v181
	v_cvt_pk_bf16_f32 v63, v74, v75
	v_cvt_pk_bf16_f32 v56, v182, v183
	v_cvt_pk_bf16_f32 v64, v80, v81
	v_cvt_pk_bf16_f32 v57, v184, v185
	v_cvt_pk_bf16_f32 v65, v82, v83
	s_branch .LBB0_446
.Lp1v_only0:
	s_setprio 1
	v_mfma_f32_16x16x32_bf16 v[170:173], v[64:67], v[2:5], 0
	v_mfma_f32_16x16x32_bf16 v[174:177], v[68:71], v[2:5], 0
	v_mfma_f32_16x16x32_bf16 v[170:173], v[54:57], v[6:9], v[170:173]
	v_mfma_f32_16x16x32_bf16 v[178:181], v[72:75], v[2:5], 0
	v_mfma_f32_16x16x32_bf16 v[174:177], v[58:61], v[6:9], v[174:177]
	v_mfma_f32_16x16x32_bf16 v[182:185], v[80:83], v[2:5], 0
	v_mfma_f32_16x16x32_bf16 v[178:181], v[76:79], v[6:9], v[178:181]
	v_mfma_f32_16x16x32_bf16 v[182:185], v[84:87], v[6:9], v[182:185]
	s_setprio 0
	s_nop 7
	s_nop 7
	s_waitcnt lgkmcnt(0)
	v_pk_fma_f32 v[170:171], v[170:171], s[36:37], v[90:91] op_sel_hi:[1,0,1]
	v_pk_fma_f32 v[172:173], v[172:173], s[36:37], v[92:93] op_sel_hi:[1,0,1]
	v_pk_fma_f32 v[174:175], v[174:175], s[36:37], v[94:95] op_sel_hi:[1,0,1]
	v_pk_fma_f32 v[176:177], v[176:177], s[36:37], v[96:97] op_sel_hi:[1,0,1]
	v_pk_fma_f32 v[178:179], v[178:179], s[36:37], v[98:99] op_sel_hi:[1,0,1]
	v_pk_fma_f32 v[180:181], v[180:181], s[36:37], v[100:101] op_sel_hi:[1,0,1]
	v_pk_fma_f32 v[182:183], v[182:183], s[36:37], v[154:155] op_sel_hi:[1,0,1]
	v_pk_fma_f32 v[184:185], v[184:185], s[36:37], v[156:157] op_sel_hi:[1,0,1]
	v_max3_f32 v186, v170, v171, v172
	v_max3_f32 v186, v186, v173, v174
	v_max3_f32 v186, v186, v175, v176
	v_max3_f32 v186, v186, v177, v178
	v_max3_f32 v186, v186, v179, v180
	v_max3_f32 v186, v186, v181, v182
	v_max3_f32 v186, v186, v183, v184
	v_max3_f32 v186, v186, v185, s29
	v_mov_b32_e32 v187, v186
	s_nop 1
	v_permlane16_swap_b32_e32 v186, v187
	v_max_f32_e32 v186, v186, v187
	v_mov_b32_e32 v187, v186
	s_nop 1
	v_permlane32_swap_b32_e32 v186, v187
	v_max_f32_e32 v186, v186, v187
	v_cndmask_b32_e64 v186, v148, v186, s[44:45]
	v_max_f32_e32 v187, v160, v186
	v_sub_f32_e32 v248, v160, v187
	v_exp_f32_e32 v236, v248
	v_cndmask_b32_e64 v246, v209, v187, s[44:45]
	v_mov_b32_e32 v160, v187
	v_pk_mul_f32 v[36:37], v[36:37], v[236:237] op_sel_hi:[1,0]
	v_pk_mul_f32 v[34:35], v[34:35], v[236:237] op_sel_hi:[1,0]
	v_pk_mul_f32 v[48:49], v[48:49], v[236:237] op_sel_hi:[1,0]
	v_pk_mul_f32 v[46:47], v[46:47], v[236:237] op_sel_hi:[1,0]
	v_pk_mul_f32 v[44:45], v[44:45], v[236:237] op_sel_hi:[1,0]
	v_pk_mul_f32 v[42:43], v[42:43], v[236:237] op_sel_hi:[1,0]
	v_pk_mul_f32 v[52:53], v[52:53], v[236:237] op_sel_hi:[1,0]
	v_pk_mul_f32 v[50:51], v[50:51], v[236:237] op_sel_hi:[1,0]
	v_pk_add_f32 v[170:171], v[170:171], v[246:247] op_sel_hi:[1,0] neg_lo:[0,1] neg_hi:[0,1]
	v_pk_add_f32 v[172:173], v[172:173], v[246:247] op_sel_hi:[1,0] neg_lo:[0,1] neg_hi:[0,1]
	v_pk_add_f32 v[174:175], v[174:175], v[246:247] op_sel_hi:[1,0] neg_lo:[0,1] neg_hi:[0,1]
	v_pk_add_f32 v[176:177], v[176:177], v[246:247] op_sel_hi:[1,0] neg_lo:[0,1] neg_hi:[0,1]
	v_pk_add_f32 v[178:179], v[178:179], v[246:247] op_sel_hi:[1,0] neg_lo:[0,1] neg_hi:[0,1]
	v_pk_add_f32 v[180:181], v[180:181], v[246:247] op_sel_hi:[1,0] neg_lo:[0,1] neg_hi:[0,1]
	v_pk_add_f32 v[182:183], v[182:183], v[246:247] op_sel_hi:[1,0] neg_lo:[0,1] neg_hi:[0,1]
	v_pk_add_f32 v[184:185], v[184:185], v[246:247] op_sel_hi:[1,0] neg_lo:[0,1] neg_hi:[0,1]
	v_exp_f32_e32 v170, v170
	v_exp_f32_e32 v171, v171
	v_exp_f32_e32 v172, v172
	v_exp_f32_e32 v173, v173
	v_exp_f32_e32 v174, v174
	v_exp_f32_e32 v175, v175
	v_exp_f32_e32 v176, v176
	v_exp_f32_e32 v177, v177
	v_exp_f32_e32 v178, v178
	v_exp_f32_e32 v179, v179
	v_exp_f32_e32 v180, v180
	v_exp_f32_e32 v181, v181
	v_exp_f32_e32 v182, v182
	v_exp_f32_e32 v183, v183
	v_exp_f32_e32 v184, v184
	v_exp_f32_e32 v185, v185
	s_nop 0
	v_pk_add_f32 v[238:239], v[170:171], v[172:173]
	v_pk_add_f32 v[240:241], v[174:175], v[176:177]
	v_pk_add_f32 v[242:243], v[178:179], v[180:181]
	v_pk_add_f32 v[244:245], v[182:183], v[184:185]
	v_pk_add_f32 v[238:239], v[238:239], v[240:241]
	v_pk_add_f32 v[242:243], v[242:243], v[244:245]
	s_nop 0
	v_pk_add_f32 v[238:239], v[238:239], v[242:243]
	s_nop 0
	v_add_f32_e32 v238, v238, v239
	v_fma_f32 v144, v144, v236, v238
	v_cvt_pk_bf16_f32 v58, v170, v171
	v_cvt_pk_bf16_f32 v59, v172, v173
	v_cvt_pk_bf16_f32 v60, v174, v175
	v_cvt_pk_bf16_f32 v61, v176, v177
	v_cvt_pk_bf16_f32 v54, v178, v179
	v_cvt_pk_bf16_f32 v55, v180, v181
	v_cvt_pk_bf16_f32 v56, v182, v183
	v_cvt_pk_bf16_f32 v57, v184, v185
	s_branch .LBB0_445
.Lp1v_m1:
	s_setprio 1
	v_mfma_f32_16x16x32_bf16 v[64:67], v[64:67], v[10:13], 0
	v_mfma_f32_16x16x32_bf16 v[68:71], v[68:71], v[10:13], 0
	v_mfma_f32_16x16x32_bf16 v[64:67], v[54:57], v[14:17], v[64:67]
	v_mfma_f32_16x16x32_bf16 v[72:75], v[72:75], v[10:13], 0
	v_mfma_f32_16x16x32_bf16 v[68:71], v[58:61], v[14:17], v[68:71]
	v_mfma_f32_16x16x32_bf16 v[80:83], v[80:83], v[10:13], 0
	v_mfma_f32_16x16x32_bf16 v[72:75], v[76:79], v[14:17], v[72:75]
	v_mfma_f32_16x16x32_bf16 v[80:83], v[84:87], v[14:17], v[80:83]
	s_setprio 0
	s_nop 7
	s_nop 7
	v_mov_b32_e32 v54, 0
	v_mov_b32_e32 v55, v54
	v_mov_b32_e32 v56, v54
	v_mov_b32_e32 v57, v54
	v_mov_b32_e32 v58, v54
	v_mov_b32_e32 v59, v54
	v_mov_b32_e32 v60, v54
	v_mov_b32_e32 v61, v54
	s_waitcnt lgkmcnt(0)
	v_pk_fma_f32 v[64:65], v[64:65], s[36:37], v[90:91] op_sel_hi:[1,0,1]
	v_pk_fma_f32 v[66:67], v[66:67], s[36:37], v[92:93] op_sel_hi:[1,0,1]
	v_pk_fma_f32 v[68:69], v[68:69], s[36:37], v[94:95] op_sel_hi:[1,0,1]
	v_pk_fma_f32 v[70:71], v[70:71], s[36:37], v[96:97] op_sel_hi:[1,0,1]
	v_pk_fma_f32 v[72:73], v[72:73], s[36:37], v[98:99] op_sel_hi:[1,0,1]
	v_pk_fma_f32 v[74:75], v[74:75], s[36:37], v[100:101] op_sel_hi:[1,0,1]
	v_pk_fma_f32 v[80:81], v[80:81], s[36:37], v[154:155] op_sel_hi:[1,0,1]
	v_pk_fma_f32 v[82:83], v[82:83], s[36:37], v[156:157] op_sel_hi:[1,0,1]
	v_max3_f32 v76, v64, v65, v66
	v_max3_f32 v76, v76, v67, v68
	v_max3_f32 v76, v76, v69, v70
	v_max3_f32 v76, v76, v71, v72
	v_max3_f32 v76, v76, v73, v74
	v_max3_f32 v76, v76, v75, v80
	v_max3_f32 v76, v76, v81, v82
	v_max3_f32 v76, v76, v83, s29
	v_mov_b32_e32 v77, v76
	s_nop 1
	v_permlane16_swap_b32_e32 v76, v77
	v_max_f32_e32 v76, v76, v77
	v_mov_b32_e32 v77, v76
	s_nop 1
	v_permlane32_swap_b32_e32 v76, v77
	v_max_f32_e32 v76, v76, v77
	v_cndmask_b32_e64 v76, v148, v76, s[42:43]
	v_max_f32_e32 v77, v161, v76
	v_sub_f32_e32 v0, v161, v77
	v_exp_f32_e32 v0, v0
	v_cndmask_b32_e64 v78, v209, v77, s[42:43]
	v_mov_b32_e32 v161, v77
	v_pk_mul_f32 v[32:33], v[32:33], v[0:1] op_sel_hi:[1,0]
	v_pk_mul_f32 v[30:31], v[30:31], v[0:1] op_sel_hi:[1,0]
	v_pk_mul_f32 v[28:29], v[28:29], v[0:1] op_sel_hi:[1,0]
	v_pk_mul_f32 v[26:27], v[26:27], v[0:1] op_sel_hi:[1,0]
	v_pk_mul_f32 v[24:25], v[24:25], v[0:1] op_sel_hi:[1,0]
	v_pk_mul_f32 v[22:23], v[22:23], v[0:1] op_sel_hi:[1,0]
	v_pk_mul_f32 v[20:21], v[20:21], v[0:1] op_sel_hi:[1,0]
	v_pk_mul_f32 v[18:19], v[18:19], v[0:1] op_sel_hi:[1,0]
	v_pk_add_f32 v[64:65], v[64:65], v[78:79] op_sel_hi:[1,0] neg_lo:[0,1] neg_hi:[0,1]
	v_pk_add_f32 v[66:67], v[66:67], v[78:79] op_sel_hi:[1,0] neg_lo:[0,1] neg_hi:[0,1]
	v_pk_add_f32 v[68:69], v[68:69], v[78:79] op_sel_hi:[1,0] neg_lo:[0,1] neg_hi:[0,1]
	v_pk_add_f32 v[70:71], v[70:71], v[78:79] op_sel_hi:[1,0] neg_lo:[0,1] neg_hi:[0,1]
	v_pk_add_f32 v[72:73], v[72:73], v[78:79] op_sel_hi:[1,0] neg_lo:[0,1] neg_hi:[0,1]
	v_pk_add_f32 v[74:75], v[74:75], v[78:79] op_sel_hi:[1,0] neg_lo:[0,1] neg_hi:[0,1]
	v_pk_add_f32 v[80:81], v[80:81], v[78:79] op_sel_hi:[1,0] neg_lo:[0,1] neg_hi:[0,1]
	v_pk_add_f32 v[82:83], v[82:83], v[78:79] op_sel_hi:[1,0] neg_lo:[0,1] neg_hi:[0,1]
	v_exp_f32_e32 v64, v64
	v_exp_f32_e32 v65, v65
	v_exp_f32_e32 v66, v66
	v_exp_f32_e32 v67, v67
	v_exp_f32_e32 v68, v68
	v_exp_f32_e32 v69, v69
	v_exp_f32_e32 v70, v70
	v_exp_f32_e32 v71, v71
	v_exp_f32_e32 v72, v72
	v_exp_f32_e32 v73, v73
	v_exp_f32_e32 v74, v74
	v_exp_f32_e32 v75, v75
	v_exp_f32_e32 v80, v80
	v_exp_f32_e32 v81, v81
	v_exp_f32_e32 v82, v82
	v_exp_f32_e32 v83, v83
	s_nop 0
	v_pk_add_f32 v[84:85], v[64:65], v[66:67]
	v_pk_add_f32 v[86:87], v[68:69], v[70:71]
	v_pk_add_f32 v[76:77], v[72:73], v[74:75]
	v_pk_add_f32 v[78:79], v[80:81], v[82:83]
	v_pk_add_f32 v[84:85], v[84:85], v[86:87]
	v_pk_add_f32 v[76:77], v[76:77], v[78:79]
	s_nop 0
	v_pk_add_f32 v[84:85], v[84:85], v[76:77]
	s_nop 0
	v_add_f32_e32 v84, v84, v85
	v_fma_f32 v145, v145, v0, v84
	v_cvt_pk_bf16_f32 v67, v66, v67
	v_cvt_pk_bf16_f32 v66, v64, v65
	v_cvt_pk_bf16_f32 v68, v68, v69
	v_cvt_pk_bf16_f32 v69, v70, v71
	v_cvt_pk_bf16_f32 v62, v72, v73
	v_cvt_pk_bf16_f32 v63, v74, v75
	v_cvt_pk_bf16_f32 v64, v80, v81
	v_cvt_pk_bf16_f32 v65, v82, v83
	s_branch .LBB0_446
